# phase-0 weight transposes: all 16 row loads of a tile in flight before the first LDS write waits (two 8-load passes unrolled)
# speedup vs baseline: 1.0099x; 1.0076x over previous
; DI unsigned pack2(float a, float b) { f32x2 v = {a, b}; bfx2 r = __builtin_convertvector(v, bfx2); return __builtin_bit_cast(unsigned, r); }
; DI void transpose_tile(const float* __restrict__ src, int ldsrc, u16* __restrict__ dst, int Kd, int k0, int n0, bool mapped, char* smem) {
;     ...
; #pragma unroll 4
;   for (int i = 0; i < 16; ++i) {
;     int k = (tid >> 6) + 4 * i;
;     float v = (sc >= 0) ? src[(size_t)(k0 + k) * ldsrc + sc] : 0.f;
;     s[k * 65 + nn] = v;
;   }
;   __syncthreads();
;   const int n = tid >> 2, kc = (tid & 3) * 16;
;   unsigned pk[8];
; #pragma unroll
;   for (int e = 0; e < 8; ++e) pk[e] = pack2(s[(kc + 2 * e) * 65 + n], s[(kc + 2 * e + 1) * 65 + n]);
;   uint4* d = (uint4*)(dst + (size_t)(n0 + n) * Kd + k0 + kc);
;   d[0] = make_uint4(pk[0], pk[1], pk[2], pk[3]);
;   d[1] = make_uint4(pk[4], pk[5], pk[6], pk[7]);
;   __syncthreads();
.LBB0_48:
	s_lshl_b32 s26, s24, 2
	s_lshl_b32 s27, s23, 2
	v_add_u32_e32 v2, s26, v28
	v_mov_b32_e32 v37, v3
	v_mov_b32_e32 v39, v3
	v_add_u32_e32 v36, s27, v19
	v_add_u32_e32 v38, s27, v23
	v_lshlrev_b64 v[56:57], 11, v[2:3]
	v_add_u32_e32 v2, s26, v30
	v_lshlrev_b64 v[36:37], 11, v[36:37]
	v_lshlrev_b64 v[38:39], 11, v[38:39]
	v_lshlrev_b64 v[58:59], 11, v[2:3]
	v_add_u32_e32 v2, s26, v32
	v_mov_b32_e32 v53, v3
	v_mov_b32_e32 v55, v3
	v_add_u32_e32 v52, s27, v25
	v_add_u32_e32 v54, s27, v29
	v_lshl_add_u64 v[56:57], v[26:27], 0, v[56:57]
	v_lshl_add_u64 v[36:37], v[26:27], 0, v[36:37]
	v_lshl_add_u64 v[38:39], v[26:27], 0, v[38:39]
	v_lshlrev_b64 v[60:61], 11, v[2:3]
	v_add_u32_e32 v2, s26, v34
	v_lshlrev_b64 v[52:53], 11, v[52:53]
	v_lshlrev_b64 v[54:55], 11, v[54:55]
	v_lshl_add_u64 v[58:59], v[26:27], 0, v[58:59]
	global_load_dword v31, v[56:57], off
	global_load_dword v33, v[36:37], off
	global_load_dword v35, v[58:59], off
	global_load_dword v51, v[38:39], off
	v_lshl_add_u64 v[36:37], v[26:27], 0, v[60:61]
	v_lshlrev_b64 v[38:39], 11, v[2:3]
	v_lshl_add_u64 v[52:53], v[26:27], 0, v[52:53]
	v_lshl_add_u64 v[54:55], v[26:27], 0, v[54:55]
	v_lshl_add_u64 v[38:39], v[26:27], 0, v[38:39]
	global_load_dword v2, v[36:37], off
	global_load_dword v64, v[52:53], off
	global_load_dword v65, v[38:39], off
	global_load_dword v66, v[54:55], off
	s_add_i32 s24, s24, 8
	s_add_i32 s23, s23, 8
	s_add_i32 s25, s25, -8
	v_add_u32_e32 v36, s26, v152
	v_add_u32_e32 v38, s27, v1
	v_add_u32_e32 v54, s27, v5
	v_add_u32_e32 v52, s26, v14
	v_add_u32_e32 v58, s27, v15
	v_add_u32_e32 v56, s26, v16
	v_add_u32_e32 v62, s27, v17
	v_add_u32_e32 v60, s26, v18
	s_cmp_lg_u32 s25, 0
	v_mad_u64_u32 v[36:37], s[26:27], v36, s33, v[4:5]
	v_mad_u64_u32 v[38:39], s[26:27], v38, s33, v[4:5]
	v_mad_u64_u32 v[52:53], s[26:27], v52, s33, v[4:5]
	v_mad_u64_u32 v[54:55], s[26:27], v54, s33, v[4:5]
	v_mad_u64_u32 v[56:57], s[26:27], v56, s33, v[4:5]
	v_mad_u64_u32 v[58:59], s[26:27], v58, s33, v[4:5]
	v_mad_u64_u32 v[60:61], s[26:27], v60, s33, v[4:5]
	v_mad_u64_u32 v[62:63], s[26:27], v62, s33, v[4:5]
	v_mov_b32_e32 v87, v3
	s_lshl_b32 s26, s24, 2
	s_lshl_b32 s27, s23, 2
	v_add_u32_e32 v86, s26, v28
	v_mov_b32_e32 v121, v3
	v_mov_b32_e32 v123, v3
	v_add_u32_e32 v120, s27, v19
	v_add_u32_e32 v122, s27, v23
	v_lshlrev_b64 v[140:141], 11, v[86:87]
	v_add_u32_e32 v86, s26, v30
	v_lshlrev_b64 v[120:121], 11, v[120:121]
	v_lshlrev_b64 v[122:123], 11, v[122:123]
	v_lshlrev_b64 v[142:143], 11, v[86:87]
	v_add_u32_e32 v86, s26, v32
	v_mov_b32_e32 v137, v3
	v_mov_b32_e32 v139, v3
	v_add_u32_e32 v136, s27, v25
	v_add_u32_e32 v138, s27, v29
	v_lshl_add_u64 v[140:141], v[26:27], 0, v[140:141]
	v_lshl_add_u64 v[120:121], v[26:27], 0, v[120:121]
	v_lshl_add_u64 v[122:123], v[26:27], 0, v[122:123]
	v_lshlrev_b64 v[144:145], 11, v[86:87]
	v_add_u32_e32 v86, s26, v34
	v_lshlrev_b64 v[136:137], 11, v[136:137]
	v_lshlrev_b64 v[138:139], 11, v[138:139]
	v_lshl_add_u64 v[142:143], v[26:27], 0, v[142:143]
	global_load_dword v115, v[140:141], off
	global_load_dword v117, v[120:121], off
	global_load_dword v119, v[142:143], off
	global_load_dword v135, v[122:123], off
	v_lshl_add_u64 v[120:121], v[26:27], 0, v[144:145]
	v_lshlrev_b64 v[122:123], 11, v[86:87]
	v_lshl_add_u64 v[136:137], v[26:27], 0, v[136:137]
	v_lshl_add_u64 v[138:139], v[26:27], 0, v[138:139]
	v_lshl_add_u64 v[122:123], v[26:27], 0, v[122:123]
	global_load_dword v86, v[120:121], off
	global_load_dword v148, v[136:137], off
	global_load_dword v149, v[122:123], off
	global_load_dword v150, v[138:139], off
	s_add_i32 s24, s24, 8
	s_add_i32 s23, s23, 8
	s_add_i32 s25, s25, -8
	v_add_u32_e32 v120, s26, v152
	v_add_u32_e32 v122, s27, v1
	v_add_u32_e32 v138, s27, v5
	v_add_u32_e32 v136, s26, v14
	v_add_u32_e32 v142, s27, v15
	v_add_u32_e32 v140, s26, v16
	v_add_u32_e32 v146, s27, v17
	v_add_u32_e32 v144, s26, v18
	s_cmp_lg_u32 s25, 0
	v_mad_u64_u32 v[120:121], s[26:27], v120, s33, v[4:5]
	v_mad_u64_u32 v[122:123], s[26:27], v122, s33, v[4:5]
	v_mad_u64_u32 v[136:137], s[26:27], v136, s33, v[4:5]
	v_mad_u64_u32 v[138:139], s[26:27], v138, s33, v[4:5]
	v_mad_u64_u32 v[140:141], s[26:27], v140, s33, v[4:5]
	v_mad_u64_u32 v[142:143], s[26:27], v142, s33, v[4:5]
	v_mad_u64_u32 v[144:145], s[26:27], v144, s33, v[4:5]
	v_mad_u64_u32 v[146:147], s[26:27], v146, s33, v[4:5]
	s_waitcnt vmcnt(15)
	ds_write_b32 v36, v31
	s_waitcnt vmcnt(14)
	ds_write_b32 v38, v33
	s_waitcnt vmcnt(13)
	ds_write_b32 v52, v35
	s_waitcnt vmcnt(12)
	ds_write_b32 v54, v51
	s_waitcnt vmcnt(11)
	ds_write_b32 v56, v2
	s_waitcnt vmcnt(10)
	ds_write_b32 v58, v64
	s_waitcnt vmcnt(9)
	ds_write_b32 v60, v65
	s_waitcnt vmcnt(8)
	ds_write_b32 v62, v66
	s_waitcnt vmcnt(7)
	ds_write_b32 v120, v115
	s_waitcnt vmcnt(6)
	ds_write_b32 v122, v117
	s_waitcnt vmcnt(5)
	ds_write_b32 v136, v119
	s_waitcnt vmcnt(4)
	ds_write_b32 v138, v135
	s_waitcnt vmcnt(3)
	ds_write_b32 v140, v86
	s_waitcnt vmcnt(2)
	ds_write_b32 v142, v148
	s_waitcnt vmcnt(1)
	ds_write_b32 v144, v149
	s_waitcnt vmcnt(0)
	ds_write_b32 v146, v150
	s_cbranch_scc1 .LBB0_48
	s_waitcnt lgkmcnt(0)
	s_barrier
	ds_read2_b32 v[26:27], v41 offset1:65
	ds_read2_b32 v[28:29], v41 offset0:130 offset1:195
	ds_read2_b32 v[30:31], v48 offset0:4 offset1:69
	v_add_u32_e32 v2, s22, v153
	s_lshl_b32 s18, s18, 1
	s_waitcnt lgkmcnt(2)
	v_cvt_pk_f16_f32 v26, v26, v27
	s_waitcnt lgkmcnt(1)
	v_cvt_pk_f16_f32 v27, v28, v29
	s_waitcnt lgkmcnt(0)
	v_cvt_pk_f16_f32 v28, v30, v31
	ds_read2_b32 v[30:31], v48 offset0:134 offset1:199
	ds_read2_b32 v[32:33], v49 offset0:8 offset1:73
	ds_read2_b32 v[34:35], v49 offset0:138 offset1:203
	ds_read2_b32 v[36:37], v50 offset0:12 offset1:77
	ds_read2_b32 v[38:39], v50 offset0:142 offset1:207
	s_waitcnt lgkmcnt(4)
	v_cvt_pk_f16_f32 v29, v30, v31
	v_mov_b32_e32 v25, v3
	s_waitcnt lgkmcnt(2)
	v_cvt_pk_f16_f32 v31, v34, v35
	v_lshlrev_b64 v[34:35], 8, v[2:3]
	v_lshl_add_u64 v[34:35], s[6:7], 0, v[34:35]
	v_lshl_add_u64 v[34:35], v[34:35], 0, s[18:19]
	v_readlane_b32 s60, v252, 38
	v_lshl_add_u64 v[34:35], v[34:35], 0, v[24:25]
	s_mov_b64 s[24:25], -1
	v_readlane_b32 s61, v252, 39
	v_readlane_b32 s62, v252, 40
	v_readlane_b32 s63, v252, 41
	v_readlane_b32 s64, v252, 42
	v_readlane_b32 s65, v252, 43
	v_readlane_b32 s66, v252, 44
	v_readlane_b32 s67, v252, 45
	v_readlane_b32 s68, v252, 46
	v_readlane_b32 s69, v252, 47
	v_readlane_b32 s70, v252, 48
	v_readlane_b32 s71, v252, 49
	v_readlane_b32 s72, v252, 50
	v_readlane_b32 s73, v252, 51
	v_readlane_b32 s74, v252, 52
	v_readlane_b32 s75, v252, 53
	v_cvt_pk_f16_f32 v30, v32, v33
	s_waitcnt lgkmcnt(1)
	v_cvt_pk_f16_f32 v32, v36, v37
	s_waitcnt lgkmcnt(0)
	v_cvt_pk_f16_f32 v33, v38, v39
	global_store_dwordx4 v[34:35], v[26:29], off
	global_store_dwordx4 v[34:35], v[30:33], off offset:16
	s_barrier

; DI unsigned pack2(float a, float b) { f32x2 v = {a, b}; bfx2 r = __builtin_convertvector(v, bfx2); return __builtin_bit_cast(unsigned, r); }
; DI void transpose_tile(const float* __restrict__ src, int ldsrc, u16* __restrict__ dst, int Kd, int k0, int n0, bool mapped, char* smem) {
;     ...
; #pragma unroll 4
;   for (int i = 0; i < 16; ++i) {
;     int k = (tid >> 6) + 4 * i;
;     float v = (sc >= 0) ? src[(size_t)(k0 + k) * ldsrc + sc] : 0.f;
;     s[k * 65 + nn] = v;
;   }
;   __syncthreads();
;   const int n = tid >> 2, kc = (tid & 3) * 16;
;   unsigned pk[8];
; #pragma unroll
;   for (int e = 0; e < 8; ++e) pk[e] = pack2(s[(kc + 2 * e) * 65 + n], s[(kc + 2 * e + 1) * 65 + n]);
;   uint4* d = (uint4*)(dst + (size_t)(n0 + n) * Kd + k0 + kc);
;   d[0] = make_uint4(pk[0], pk[1], pk[2], pk[3]);
;   d[1] = make_uint4(pk[4], pk[5], pk[6], pk[7]);
;   __syncthreads();
.LBB0_52:
	s_lshl_b32 s25, s23, 2
	s_lshl_b32 s26, s22, 2
	v_add_u32_e32 v2, s25, v152
	v_add_u32_e32 v28, s26, v1
	v_add_u32_e32 v30, s26, v5
	v_add_u32_e32 v32, s26, v15
	v_add_u32_e32 v34, s26, v17
	v_lshlrev_b64 v[38:39], 11, v[2:3]
	v_mad_u64_u32 v[52:53], s[26:27], v2, s33, v[4:5]
	v_add_u32_e32 v2, s25, v14
	v_mov_b32_e32 v29, v3
	v_mov_b32_e32 v31, v3
	v_lshlrev_b64 v[60:61], 11, v[2:3]
	v_mad_u64_u32 v[62:63], s[26:27], v2, s33, v[4:5]
	v_add_u32_e32 v2, s25, v16
	v_lshlrev_b64 v[36:37], 11, v[28:29]
	v_lshlrev_b64 v[54:55], 11, v[30:31]
	v_lshl_add_u64 v[38:39], v[26:27], 0, v[38:39]
	v_lshlrev_b64 v[64:65], 11, v[2:3]
	v_mad_u64_u32 v[66:67], s[26:27], v2, s33, v[4:5]
	v_add_u32_e32 v2, s25, v18
	v_mov_b32_e32 v33, v3
	v_mov_b32_e32 v35, v3
	v_lshl_add_u64 v[36:37], v[26:27], 0, v[36:37]
	v_lshl_add_u64 v[54:55], v[26:27], 0, v[54:55]
	v_lshl_add_u64 v[60:61], v[26:27], 0, v[60:61]
	global_load_dword v19, v[38:39], off
	global_load_dword v23, v[36:37], off
	global_load_dword v25, v[60:61], off
	global_load_dword v51, v[54:55], off
	v_lshlrev_b64 v[38:39], 11, v[2:3]
	v_lshlrev_b64 v[56:57], 11, v[32:33]
	v_lshlrev_b64 v[58:59], 11, v[34:35]
	v_lshl_add_u64 v[36:37], v[26:27], 0, v[64:65]
	v_lshl_add_u64 v[38:39], v[26:27], 0, v[38:39]
	v_lshl_add_u64 v[56:57], v[26:27], 0, v[56:57]
	v_lshl_add_u64 v[58:59], v[26:27], 0, v[58:59]
	global_load_dword v53, v[36:37], off
	global_load_dword v54, v[56:57], off
	s_nop 0
	global_load_dword v38, v[38:39], off
	s_nop 0
	global_load_dword v39, v[58:59], off
	s_add_i32 s23, s23, 8
	s_add_i32 s22, s22, 8
	s_add_i32 s24, s24, -8
	s_cmp_lg_u32 s24, 0
	v_mad_u64_u32 v[28:29], s[26:27], v28, s33, v[4:5]
	v_mad_u64_u32 v[30:31], s[26:27], v30, s33, v[4:5]
	v_mad_u64_u32 v[32:33], s[26:27], v32, s33, v[4:5]
	v_mad_u64_u32 v[34:35], s[26:27], v34, s33, v[4:5]
	v_mad_u64_u32 v[36:37], s[26:27], v2, s33, v[4:5]
	v_mov_b32_e32 v87, v3
	s_lshl_b32 s25, s23, 2
	s_lshl_b32 s26, s22, 2
	v_add_u32_e32 v86, s25, v152
	v_add_u32_e32 v112, s26, v1
	v_add_u32_e32 v114, s26, v5
	v_add_u32_e32 v116, s26, v15
	v_add_u32_e32 v118, s26, v17
	v_lshlrev_b64 v[122:123], 11, v[86:87]
	v_mad_u64_u32 v[136:137], s[26:27], v86, s33, v[4:5]
	v_add_u32_e32 v86, s25, v14
	v_mov_b32_e32 v113, v3
	v_mov_b32_e32 v115, v3
	v_lshlrev_b64 v[144:145], 11, v[86:87]
	v_mad_u64_u32 v[146:147], s[26:27], v86, s33, v[4:5]
	v_add_u32_e32 v86, s25, v16
	v_lshlrev_b64 v[120:121], 11, v[112:113]
	v_lshlrev_b64 v[138:139], 11, v[114:115]
	v_lshl_add_u64 v[122:123], v[26:27], 0, v[122:123]
	v_lshlrev_b64 v[148:149], 11, v[86:87]
	v_mad_u64_u32 v[150:151], s[26:27], v86, s33, v[4:5]
	v_add_u32_e32 v86, s25, v18
	v_mov_b32_e32 v117, v3
	v_mov_b32_e32 v119, v3
	v_lshl_add_u64 v[120:121], v[26:27], 0, v[120:121]
	v_lshl_add_u64 v[138:139], v[26:27], 0, v[138:139]
	v_lshl_add_u64 v[144:145], v[26:27], 0, v[144:145]
	global_load_dword v103, v[122:123], off
	global_load_dword v107, v[120:121], off
	global_load_dword v109, v[144:145], off
	global_load_dword v135, v[138:139], off
	v_lshlrev_b64 v[122:123], 11, v[86:87]
	v_lshlrev_b64 v[140:141], 11, v[116:117]
	v_lshlrev_b64 v[142:143], 11, v[118:119]
	v_lshl_add_u64 v[120:121], v[26:27], 0, v[148:149]
	v_lshl_add_u64 v[122:123], v[26:27], 0, v[122:123]
	v_lshl_add_u64 v[140:141], v[26:27], 0, v[140:141]
	v_lshl_add_u64 v[142:143], v[26:27], 0, v[142:143]
	global_load_dword v137, v[120:121], off
	global_load_dword v138, v[140:141], off
	s_nop 0
	global_load_dword v122, v[122:123], off
	s_nop 0
	global_load_dword v123, v[142:143], off
	s_add_i32 s23, s23, 8
	s_add_i32 s22, s22, 8
	s_add_i32 s24, s24, -8
	s_cmp_lg_u32 s24, 0
	v_mad_u64_u32 v[112:113], s[26:27], v112, s33, v[4:5]
	v_mad_u64_u32 v[114:115], s[26:27], v114, s33, v[4:5]
	v_mad_u64_u32 v[116:117], s[26:27], v116, s33, v[4:5]
	v_mad_u64_u32 v[118:119], s[26:27], v118, s33, v[4:5]
	v_mad_u64_u32 v[120:121], s[26:27], v86, s33, v[4:5]
	s_waitcnt vmcnt(15)
	ds_write_b32 v52, v19
	s_waitcnt vmcnt(14)
	ds_write_b32 v28, v23
	s_waitcnt vmcnt(13)
	ds_write_b32 v62, v25
	s_waitcnt vmcnt(12)
	ds_write_b32 v30, v51
	s_waitcnt vmcnt(11)
	ds_write_b32 v66, v53
	s_waitcnt vmcnt(10)
	ds_write_b32 v32, v54
	s_waitcnt vmcnt(9)
	ds_write_b32 v36, v38
	s_waitcnt vmcnt(8)
	ds_write_b32 v34, v39
	s_waitcnt vmcnt(7)
	ds_write_b32 v136, v103
	s_waitcnt vmcnt(6)
	ds_write_b32 v112, v107
	s_waitcnt vmcnt(5)
	ds_write_b32 v146, v109
	s_waitcnt vmcnt(4)
	ds_write_b32 v114, v135
	s_waitcnt vmcnt(3)
	ds_write_b32 v150, v137
	s_waitcnt vmcnt(2)
	ds_write_b32 v116, v138
	s_waitcnt vmcnt(1)
	ds_write_b32 v120, v122
	s_waitcnt vmcnt(0)
	ds_write_b32 v118, v123
	s_cbranch_scc1 .LBB0_52
	s_waitcnt lgkmcnt(0)
	s_barrier
	ds_read2_b32 v[26:27], v41 offset1:65
	ds_read2_b32 v[28:29], v41 offset0:130 offset1:195
	ds_read2_b32 v[30:31], v48 offset0:4 offset1:69
	v_add_u32_e32 v2, s18, v153
	v_readlane_b32 s60, v252, 38
	s_waitcnt lgkmcnt(2)
	v_cvt_pk_f16_f32 v26, v26, v27
	s_waitcnt lgkmcnt(1)
	v_cvt_pk_f16_f32 v27, v28, v29
	s_waitcnt lgkmcnt(0)
	v_cvt_pk_f16_f32 v28, v30, v31
	ds_read2_b32 v[30:31], v48 offset0:134 offset1:199
	ds_read2_b32 v[32:33], v49 offset0:8 offset1:73
	ds_read2_b32 v[34:35], v49 offset0:138 offset1:203
	ds_read2_b32 v[36:37], v50 offset0:12 offset1:77
	ds_read2_b32 v[38:39], v50 offset0:142 offset1:207
	s_waitcnt lgkmcnt(4)
	v_cvt_pk_f16_f32 v29, v30, v31
	s_mov_b64 s[24:25], -1
	s_waitcnt lgkmcnt(2)
	v_cvt_pk_f16_f32 v31, v34, v35
	v_lshlrev_b64 v[34:35], 7, v[2:3]
	v_lshl_add_u64 v[34:35], v[6:7], 0, v[34:35]
	v_readlane_b32 s61, v252, 39
	v_readlane_b32 s62, v252, 40
	v_readlane_b32 s63, v252, 41
	v_readlane_b32 s64, v252, 42
	v_readlane_b32 s65, v252, 43
	v_readlane_b32 s66, v252, 44
	v_readlane_b32 s67, v252, 45
	v_readlane_b32 s68, v252, 46
	v_readlane_b32 s69, v252, 47
	v_readlane_b32 s70, v252, 48
	v_readlane_b32 s71, v252, 49
	v_readlane_b32 s72, v252, 50
	v_readlane_b32 s73, v252, 51
	v_readlane_b32 s74, v252, 52
	v_readlane_b32 s75, v252, 53
	v_cvt_pk_f16_f32 v30, v32, v33
	s_waitcnt lgkmcnt(1)
	v_cvt_pk_f16_f32 v32, v36, v37
	s_waitcnt lgkmcnt(0)
	v_cvt_pk_f16_f32 v33, v38, v39
	global_store_dwordx4 v[34:35], v[26:29], off
	global_store_dwordx4 v[34:35], v[30:33], off offset:16
	s_barrier

; DI unsigned pack2(float a, float b) { f32x2 v = {a, b}; bfx2 r = __builtin_convertvector(v, bfx2); return __builtin_bit_cast(unsigned, r); }
; DI void transpose_tile(const float* __restrict__ src, int ldsrc, u16* __restrict__ dst, int Kd, int k0, int n0, bool mapped, char* smem) {
;     ...
; #pragma unroll 4
;   for (int i = 0; i < 16; ++i) {
;     int k = (tid >> 6) + 4 * i;
;     float v = (sc >= 0) ? src[(size_t)(k0 + k) * ldsrc + sc] : 0.f;
;     s[k * 65 + nn] = v;
;   }
;   __syncthreads();
;   const int n = tid >> 2, kc = (tid & 3) * 16;
;   unsigned pk[8];
; #pragma unroll
;   for (int e = 0; e < 8; ++e) pk[e] = pack2(s[(kc + 2 * e) * 65 + n], s[(kc + 2 * e + 1) * 65 + n]);
;   uint4* d = (uint4*)(dst + (size_t)(n0 + n) * Kd + k0 + kc);
;   d[0] = make_uint4(pk[0], pk[1], pk[2], pk[3]);
;   d[1] = make_uint4(pk[4], pk[5], pk[6], pk[7]);
;   __syncthreads();
.LBB0_56:
	s_lshl_b32 s25, s23, 2
	s_lshl_b32 s26, s22, 2
	v_add_u32_e32 v2, s25, v152
	v_add_u32_e32 v28, s26, v1
	v_add_u32_e32 v30, s26, v5
	v_add_u32_e32 v32, s26, v15
	v_add_u32_e32 v34, s26, v17
	v_lshlrev_b64 v[38:39], 11, v[2:3]
	v_mad_u64_u32 v[52:53], s[26:27], v2, s33, v[4:5]
	v_add_u32_e32 v2, s25, v14
	v_mov_b32_e32 v29, v3
	v_mov_b32_e32 v31, v3
	v_lshlrev_b64 v[60:61], 11, v[2:3]
	v_mad_u64_u32 v[62:63], s[26:27], v2, s33, v[4:5]
	v_add_u32_e32 v2, s25, v16
	v_lshlrev_b64 v[36:37], 11, v[28:29]
	v_lshlrev_b64 v[54:55], 11, v[30:31]
	v_lshl_add_u64 v[38:39], v[26:27], 0, v[38:39]
	v_lshlrev_b64 v[64:65], 11, v[2:3]
	v_mad_u64_u32 v[66:67], s[26:27], v2, s33, v[4:5]
	v_add_u32_e32 v2, s25, v18
	v_mov_b32_e32 v33, v3
	v_mov_b32_e32 v35, v3
	v_lshl_add_u64 v[36:37], v[26:27], 0, v[36:37]
	v_lshl_add_u64 v[54:55], v[26:27], 0, v[54:55]
	v_lshl_add_u64 v[60:61], v[26:27], 0, v[60:61]
	global_load_dword v19, v[38:39], off
	global_load_dword v23, v[36:37], off
	global_load_dword v25, v[60:61], off
	global_load_dword v51, v[54:55], off
	v_lshlrev_b64 v[38:39], 11, v[2:3]
	v_lshlrev_b64 v[56:57], 11, v[32:33]
	v_lshlrev_b64 v[58:59], 11, v[34:35]
	v_lshl_add_u64 v[36:37], v[26:27], 0, v[64:65]
	v_lshl_add_u64 v[38:39], v[26:27], 0, v[38:39]
	v_lshl_add_u64 v[56:57], v[26:27], 0, v[56:57]
	v_lshl_add_u64 v[58:59], v[26:27], 0, v[58:59]
	global_load_dword v53, v[36:37], off
	global_load_dword v54, v[56:57], off
	s_nop 0
	global_load_dword v38, v[38:39], off
	s_nop 0
	global_load_dword v39, v[58:59], off
	s_add_i32 s23, s23, 8
	s_add_i32 s22, s22, 8
	s_add_i32 s24, s24, -8
	s_cmp_lg_u32 s24, 0
	v_mad_u64_u32 v[28:29], s[26:27], v28, s33, v[4:5]
	v_mad_u64_u32 v[30:31], s[26:27], v30, s33, v[4:5]
	v_mad_u64_u32 v[32:33], s[26:27], v32, s33, v[4:5]
	v_mad_u64_u32 v[34:35], s[26:27], v34, s33, v[4:5]
	v_mad_u64_u32 v[36:37], s[26:27], v2, s33, v[4:5]
	v_mov_b32_e32 v87, v3
	s_lshl_b32 s25, s23, 2
	s_lshl_b32 s26, s22, 2
	v_add_u32_e32 v86, s25, v152
	v_add_u32_e32 v112, s26, v1
	v_add_u32_e32 v114, s26, v5
	v_add_u32_e32 v116, s26, v15
	v_add_u32_e32 v118, s26, v17
	v_lshlrev_b64 v[122:123], 11, v[86:87]
	v_mad_u64_u32 v[136:137], s[26:27], v86, s33, v[4:5]
	v_add_u32_e32 v86, s25, v14
	v_mov_b32_e32 v113, v3
	v_mov_b32_e32 v115, v3
	v_lshlrev_b64 v[144:145], 11, v[86:87]
	v_mad_u64_u32 v[146:147], s[26:27], v86, s33, v[4:5]
	v_add_u32_e32 v86, s25, v16
	v_lshlrev_b64 v[120:121], 11, v[112:113]
	v_lshlrev_b64 v[138:139], 11, v[114:115]
	v_lshl_add_u64 v[122:123], v[26:27], 0, v[122:123]
	v_lshlrev_b64 v[148:149], 11, v[86:87]
	v_mad_u64_u32 v[150:151], s[26:27], v86, s33, v[4:5]
	v_add_u32_e32 v86, s25, v18
	v_mov_b32_e32 v117, v3
	v_mov_b32_e32 v119, v3
	v_lshl_add_u64 v[120:121], v[26:27], 0, v[120:121]
	v_lshl_add_u64 v[138:139], v[26:27], 0, v[138:139]
	v_lshl_add_u64 v[144:145], v[26:27], 0, v[144:145]
	global_load_dword v103, v[122:123], off
	global_load_dword v107, v[120:121], off
	global_load_dword v109, v[144:145], off
	global_load_dword v135, v[138:139], off
	v_lshlrev_b64 v[122:123], 11, v[86:87]
	v_lshlrev_b64 v[140:141], 11, v[116:117]
	v_lshlrev_b64 v[142:143], 11, v[118:119]
	v_lshl_add_u64 v[120:121], v[26:27], 0, v[148:149]
	v_lshl_add_u64 v[122:123], v[26:27], 0, v[122:123]
	v_lshl_add_u64 v[140:141], v[26:27], 0, v[140:141]
	v_lshl_add_u64 v[142:143], v[26:27], 0, v[142:143]
	global_load_dword v137, v[120:121], off
	global_load_dword v138, v[140:141], off
	s_nop 0
	global_load_dword v122, v[122:123], off
	s_nop 0
	global_load_dword v123, v[142:143], off
	s_add_i32 s23, s23, 8
	s_add_i32 s22, s22, 8
	s_add_i32 s24, s24, -8
	s_cmp_lg_u32 s24, 0
	v_mad_u64_u32 v[112:113], s[26:27], v112, s33, v[4:5]
	v_mad_u64_u32 v[114:115], s[26:27], v114, s33, v[4:5]
	v_mad_u64_u32 v[116:117], s[26:27], v116, s33, v[4:5]
	v_mad_u64_u32 v[118:119], s[26:27], v118, s33, v[4:5]
	v_mad_u64_u32 v[120:121], s[26:27], v86, s33, v[4:5]
	s_waitcnt vmcnt(15)
	ds_write_b32 v52, v19
	s_waitcnt vmcnt(14)
	ds_write_b32 v28, v23
	s_waitcnt vmcnt(13)
	ds_write_b32 v62, v25
	s_waitcnt vmcnt(12)
	ds_write_b32 v30, v51
	s_waitcnt vmcnt(11)
	ds_write_b32 v66, v53
	s_waitcnt vmcnt(10)
	ds_write_b32 v32, v54
	s_waitcnt vmcnt(9)
	ds_write_b32 v36, v38
	s_waitcnt vmcnt(8)
	ds_write_b32 v34, v39
	s_waitcnt vmcnt(7)
	ds_write_b32 v136, v103
	s_waitcnt vmcnt(6)
	ds_write_b32 v112, v107
	s_waitcnt vmcnt(5)
	ds_write_b32 v146, v109
	s_waitcnt vmcnt(4)
	ds_write_b32 v114, v135
	s_waitcnt vmcnt(3)
	ds_write_b32 v150, v137
	s_waitcnt vmcnt(2)
	ds_write_b32 v116, v138
	s_waitcnt vmcnt(1)
	ds_write_b32 v120, v122
	s_waitcnt vmcnt(0)
	ds_write_b32 v118, v123
	s_cbranch_scc1 .LBB0_56
	s_waitcnt lgkmcnt(0)
	s_barrier
	ds_read2_b32 v[26:27], v41 offset1:65
	ds_read2_b32 v[28:29], v41 offset0:130 offset1:195
	ds_read2_b32 v[30:31], v48 offset0:4 offset1:69
	v_add_u32_e32 v2, s18, v153
	v_readlane_b32 s60, v252, 38
	s_waitcnt lgkmcnt(2)
	v_cvt_pk_f16_f32 v26, v26, v27
	s_waitcnt lgkmcnt(1)
	v_cvt_pk_f16_f32 v27, v28, v29
	s_waitcnt lgkmcnt(0)
	v_cvt_pk_f16_f32 v28, v30, v31
	ds_read2_b32 v[30:31], v48 offset0:134 offset1:199
	ds_read2_b32 v[32:33], v49 offset0:8 offset1:73
	ds_read2_b32 v[34:35], v49 offset0:138 offset1:203
	ds_read2_b32 v[36:37], v50 offset0:12 offset1:77
	ds_read2_b32 v[38:39], v50 offset0:142 offset1:207
	s_waitcnt lgkmcnt(4)
	v_cvt_pk_f16_f32 v29, v30, v31
	s_mov_b64 s[24:25], -1
	s_waitcnt lgkmcnt(2)
	v_cvt_pk_f16_f32 v31, v34, v35
	v_lshlrev_b64 v[34:35], 7, v[2:3]
	v_lshl_add_u64 v[34:35], v[8:9], 0, v[34:35]
	v_readlane_b32 s61, v252, 39
	v_readlane_b32 s62, v252, 40
	v_readlane_b32 s63, v252, 41
	v_readlane_b32 s64, v252, 42
	v_readlane_b32 s65, v252, 43
	v_readlane_b32 s66, v252, 44
	v_readlane_b32 s67, v252, 45
	v_readlane_b32 s68, v252, 46
	v_readlane_b32 s69, v252, 47
	v_readlane_b32 s70, v252, 48
	v_readlane_b32 s71, v252, 49
	v_readlane_b32 s72, v252, 50
	v_readlane_b32 s73, v252, 51
	v_readlane_b32 s74, v252, 52
	v_readlane_b32 s75, v252, 53
	v_cvt_pk_f16_f32 v30, v32, v33
	s_waitcnt lgkmcnt(1)
	v_cvt_pk_f16_f32 v32, v36, v37
	s_waitcnt lgkmcnt(0)
	v_cvt_pk_f16_f32 v33, v38, v39
	global_store_dwordx4 v[34:35], v[26:29], off
	global_store_dwordx4 v[34:35], v[30:33], off offset:16
	s_barrier

; DI unsigned pack2(float a, float b) { f32x2 v = {a, b}; bfx2 r = __builtin_convertvector(v, bfx2); return __builtin_bit_cast(unsigned, r); }
; DI void transpose_tile(const float* __restrict__ src, int ldsrc, u16* __restrict__ dst, int Kd, int k0, int n0, bool mapped, char* smem) {
;     ...
; #pragma unroll 4
;   for (int i = 0; i < 16; ++i) {
;     int k = (tid >> 6) + 4 * i;
;     float v = (sc >= 0) ? src[(size_t)(k0 + k) * ldsrc + sc] : 0.f;
;     s[k * 65 + nn] = v;
;   }
;   __syncthreads();
;   const int n = tid >> 2, kc = (tid & 3) * 16;
;   unsigned pk[8];
; #pragma unroll
;   for (int e = 0; e < 8; ++e) pk[e] = pack2(s[(kc + 2 * e) * 65 + n], s[(kc + 2 * e + 1) * 65 + n]);
;   uint4* d = (uint4*)(dst + (size_t)(n0 + n) * Kd + k0 + kc);
;   d[0] = make_uint4(pk[0], pk[1], pk[2], pk[3]);
;   d[1] = make_uint4(pk[4], pk[5], pk[6], pk[7]);
;   __syncthreads();
.LBB0_60:
	s_lshl_b32 s26, s24, 2
	s_lshl_b32 s27, s23, 2
	v_add_u32_e32 v2, s26, v28
	v_mov_b32_e32 v37, v3
	v_mov_b32_e32 v39, v3
	v_add_u32_e32 v36, s27, v19
	v_add_u32_e32 v38, s27, v23
	v_lshlrev_b64 v[56:57], 9, v[2:3]
	v_add_u32_e32 v2, s26, v30
	v_lshlrev_b64 v[36:37], 9, v[36:37]
	v_lshlrev_b64 v[38:39], 9, v[38:39]
	v_lshlrev_b64 v[58:59], 9, v[2:3]
	v_add_u32_e32 v2, s26, v32
	v_mov_b32_e32 v53, v3
	v_mov_b32_e32 v55, v3
	v_add_u32_e32 v52, s27, v25
	v_add_u32_e32 v54, s27, v29
	v_lshl_add_u64 v[56:57], v[26:27], 0, v[56:57]
	v_lshl_add_u64 v[36:37], v[26:27], 0, v[36:37]
	v_lshl_add_u64 v[38:39], v[26:27], 0, v[38:39]
	v_lshlrev_b64 v[60:61], 9, v[2:3]
	v_add_u32_e32 v2, s26, v34
	v_lshlrev_b64 v[52:53], 9, v[52:53]
	v_lshlrev_b64 v[54:55], 9, v[54:55]
	v_lshl_add_u64 v[58:59], v[26:27], 0, v[58:59]
	global_load_dword v31, v[56:57], off
	global_load_dword v33, v[36:37], off
	global_load_dword v35, v[58:59], off
	global_load_dword v51, v[38:39], off
	v_lshl_add_u64 v[36:37], v[26:27], 0, v[60:61]
	v_lshlrev_b64 v[38:39], 9, v[2:3]
	v_lshl_add_u64 v[52:53], v[26:27], 0, v[52:53]
	v_lshl_add_u64 v[54:55], v[26:27], 0, v[54:55]
	v_lshl_add_u64 v[38:39], v[26:27], 0, v[38:39]
	global_load_dword v2, v[36:37], off
	global_load_dword v64, v[52:53], off
	global_load_dword v65, v[38:39], off
	global_load_dword v66, v[54:55], off
	s_add_i32 s24, s24, 8
	s_add_i32 s23, s23, 8
	s_add_i32 s25, s25, -8
	v_add_u32_e32 v36, s26, v152
	v_add_u32_e32 v38, s27, v1
	v_add_u32_e32 v54, s27, v5
	v_add_u32_e32 v52, s26, v14
	v_add_u32_e32 v58, s27, v15
	v_add_u32_e32 v56, s26, v16
	v_add_u32_e32 v62, s27, v17
	v_add_u32_e32 v60, s26, v18
	s_cmp_lg_u32 s25, 0
	v_mad_u64_u32 v[36:37], s[26:27], v36, s33, v[4:5]
	v_mad_u64_u32 v[38:39], s[26:27], v38, s33, v[4:5]
	v_mad_u64_u32 v[52:53], s[26:27], v52, s33, v[4:5]
	v_mad_u64_u32 v[54:55], s[26:27], v54, s33, v[4:5]
	v_mad_u64_u32 v[56:57], s[26:27], v56, s33, v[4:5]
	v_mad_u64_u32 v[58:59], s[26:27], v58, s33, v[4:5]
	v_mad_u64_u32 v[60:61], s[26:27], v60, s33, v[4:5]
	v_mad_u64_u32 v[62:63], s[26:27], v62, s33, v[4:5]
	v_mov_b32_e32 v87, v3
	s_lshl_b32 s26, s24, 2
	s_lshl_b32 s27, s23, 2
	v_add_u32_e32 v86, s26, v28
	v_mov_b32_e32 v121, v3
	v_mov_b32_e32 v123, v3
	v_add_u32_e32 v120, s27, v19
	v_add_u32_e32 v122, s27, v23
	v_lshlrev_b64 v[140:141], 9, v[86:87]
	v_add_u32_e32 v86, s26, v30
	v_lshlrev_b64 v[120:121], 9, v[120:121]
	v_lshlrev_b64 v[122:123], 9, v[122:123]
	v_lshlrev_b64 v[142:143], 9, v[86:87]
	v_add_u32_e32 v86, s26, v32
	v_mov_b32_e32 v137, v3
	v_mov_b32_e32 v139, v3
	v_add_u32_e32 v136, s27, v25
	v_add_u32_e32 v138, s27, v29
	v_lshl_add_u64 v[140:141], v[26:27], 0, v[140:141]
	v_lshl_add_u64 v[120:121], v[26:27], 0, v[120:121]
	v_lshl_add_u64 v[122:123], v[26:27], 0, v[122:123]
	v_lshlrev_b64 v[144:145], 9, v[86:87]
	v_add_u32_e32 v86, s26, v34
	v_lshlrev_b64 v[136:137], 9, v[136:137]
	v_lshlrev_b64 v[138:139], 9, v[138:139]
	v_lshl_add_u64 v[142:143], v[26:27], 0, v[142:143]
	global_load_dword v115, v[140:141], off
	global_load_dword v117, v[120:121], off
	global_load_dword v119, v[142:143], off
	global_load_dword v135, v[122:123], off
	v_lshl_add_u64 v[120:121], v[26:27], 0, v[144:145]
	v_lshlrev_b64 v[122:123], 9, v[86:87]
	v_lshl_add_u64 v[136:137], v[26:27], 0, v[136:137]
	v_lshl_add_u64 v[138:139], v[26:27], 0, v[138:139]
	v_lshl_add_u64 v[122:123], v[26:27], 0, v[122:123]
	global_load_dword v86, v[120:121], off
	global_load_dword v148, v[136:137], off
	global_load_dword v149, v[122:123], off
	global_load_dword v150, v[138:139], off
	s_add_i32 s24, s24, 8
	s_add_i32 s23, s23, 8
	s_add_i32 s25, s25, -8
	v_add_u32_e32 v120, s26, v152
	v_add_u32_e32 v122, s27, v1
	v_add_u32_e32 v138, s27, v5
	v_add_u32_e32 v136, s26, v14
	v_add_u32_e32 v142, s27, v15
	v_add_u32_e32 v140, s26, v16
	v_add_u32_e32 v146, s27, v17
	v_add_u32_e32 v144, s26, v18
	s_cmp_lg_u32 s25, 0
	v_mad_u64_u32 v[120:121], s[26:27], v120, s33, v[4:5]
	v_mad_u64_u32 v[122:123], s[26:27], v122, s33, v[4:5]
	v_mad_u64_u32 v[136:137], s[26:27], v136, s33, v[4:5]
	v_mad_u64_u32 v[138:139], s[26:27], v138, s33, v[4:5]
	v_mad_u64_u32 v[140:141], s[26:27], v140, s33, v[4:5]
	v_mad_u64_u32 v[142:143], s[26:27], v142, s33, v[4:5]
	v_mad_u64_u32 v[144:145], s[26:27], v144, s33, v[4:5]
	v_mad_u64_u32 v[146:147], s[26:27], v146, s33, v[4:5]
	s_waitcnt vmcnt(15)
	ds_write_b32 v36, v31
	s_waitcnt vmcnt(14)
	ds_write_b32 v38, v33
	s_waitcnt vmcnt(13)
	ds_write_b32 v52, v35
	s_waitcnt vmcnt(12)
	ds_write_b32 v54, v51
	s_waitcnt vmcnt(11)
	ds_write_b32 v56, v2
	s_waitcnt vmcnt(10)
	ds_write_b32 v58, v64
	s_waitcnt vmcnt(9)
	ds_write_b32 v60, v65
	s_waitcnt vmcnt(8)
	ds_write_b32 v62, v66
	s_waitcnt vmcnt(7)
	ds_write_b32 v120, v115
	s_waitcnt vmcnt(6)
	ds_write_b32 v122, v117
	s_waitcnt vmcnt(5)
	ds_write_b32 v136, v119
	s_waitcnt vmcnt(4)
	ds_write_b32 v138, v135
	s_waitcnt vmcnt(3)
	ds_write_b32 v140, v86
	s_waitcnt vmcnt(2)
	ds_write_b32 v142, v148
	s_waitcnt vmcnt(1)
	ds_write_b32 v144, v149
	s_waitcnt vmcnt(0)
	ds_write_b32 v146, v150
	s_cbranch_scc1 .LBB0_60
	s_waitcnt lgkmcnt(0)
	s_barrier
	ds_read2_b32 v[26:27], v41 offset1:65
	ds_read2_b32 v[28:29], v41 offset0:130 offset1:195
	ds_read2_b32 v[30:31], v48 offset0:4 offset1:69
	v_add_u32_e32 v2, s22, v153
	s_lshl_b32 s18, s18, 1
	s_waitcnt lgkmcnt(2)
	v_cvt_pk_f16_f32 v26, v26, v27
	s_waitcnt lgkmcnt(1)
	v_cvt_pk_f16_f32 v27, v28, v29
	s_waitcnt lgkmcnt(0)
	v_cvt_pk_f16_f32 v28, v30, v31
	ds_read2_b32 v[30:31], v48 offset0:134 offset1:199
	ds_read2_b32 v[32:33], v49 offset0:8 offset1:73
	ds_read2_b32 v[34:35], v49 offset0:138 offset1:203
	ds_read2_b32 v[36:37], v50 offset0:12 offset1:77
	ds_read2_b32 v[38:39], v50 offset0:142 offset1:207
	s_waitcnt lgkmcnt(4)
	v_cvt_pk_f16_f32 v29, v30, v31
	v_mov_b32_e32 v25, v3
	s_waitcnt lgkmcnt(2)
	v_cvt_pk_f16_f32 v31, v34, v35
	v_lshlrev_b64 v[34:35], 12, v[2:3]
	v_lshl_add_u64 v[34:35], s[8:9], 0, v[34:35]
	v_lshl_add_u64 v[34:35], v[34:35], 0, s[18:19]
	v_lshl_add_u64 v[34:35], v[34:35], 0, v[24:25]
	s_mov_b64 s[24:25], -1
	v_cvt_pk_f16_f32 v30, v32, v33
	s_waitcnt lgkmcnt(1)
	v_cvt_pk_f16_f32 v32, v36, v37
	s_waitcnt lgkmcnt(0)
	v_cvt_pk_f16_f32 v33, v38, v39
	global_store_dwordx4 v[34:35], v[26:29], off
	global_store_dwordx4 v[34:35], v[30:33], off offset:16
	s_barrier

; DI unsigned pack2(float a, float b) { f32x2 v = {a, b}; bfx2 r = __builtin_convertvector(v, bfx2); return __builtin_bit_cast(unsigned, r); }
; DI void transpose_tile(const float* __restrict__ src, int ldsrc, u16* __restrict__ dst, int Kd, int k0, int n0, bool mapped, char* smem) {
;     ...
; #pragma unroll 4
;   for (int i = 0; i < 16; ++i) {
;     int k = (tid >> 6) + 4 * i;
;     float v = (sc >= 0) ? src[(size_t)(k0 + k) * ldsrc + sc] : 0.f;
;     s[k * 65 + nn] = v;
;   }
;   __syncthreads();
;   const int n = tid >> 2, kc = (tid & 3) * 16;
;   unsigned pk[8];
; #pragma unroll
;   for (int e = 0; e < 8; ++e) pk[e] = pack2(s[(kc + 2 * e) * 65 + n], s[(kc + 2 * e + 1) * 65 + n]);
;   uint4* d = (uint4*)(dst + (size_t)(n0 + n) * Kd + k0 + kc);
;   d[0] = make_uint4(pk[0], pk[1], pk[2], pk[3]);
;   d[1] = make_uint4(pk[4], pk[5], pk[6], pk[7]);
;   __syncthreads();
.LBB0_64:
	s_lshl_b32 s26, s24, 2
	s_lshl_b32 s27, s23, 2
	v_add_u32_e32 v2, s26, v28
	v_mov_b32_e32 v37, v3
	v_mov_b32_e32 v39, v3
	v_add_u32_e32 v36, s27, v19
	v_add_u32_e32 v38, s27, v23
	v_lshlrev_b64 v[56:57], 9, v[2:3]
	v_add_u32_e32 v2, s26, v30
	v_lshlrev_b64 v[36:37], 9, v[36:37]
	v_lshlrev_b64 v[38:39], 9, v[38:39]
	v_lshlrev_b64 v[58:59], 9, v[2:3]
	v_add_u32_e32 v2, s26, v32
	v_mov_b32_e32 v53, v3
	v_mov_b32_e32 v55, v3
	v_add_u32_e32 v52, s27, v25
	v_add_u32_e32 v54, s27, v29
	v_lshl_add_u64 v[56:57], v[26:27], 0, v[56:57]
	v_lshl_add_u64 v[36:37], v[26:27], 0, v[36:37]
	v_lshl_add_u64 v[38:39], v[26:27], 0, v[38:39]
	v_lshlrev_b64 v[60:61], 9, v[2:3]
	v_add_u32_e32 v2, s26, v34
	v_lshlrev_b64 v[52:53], 9, v[52:53]
	v_lshlrev_b64 v[54:55], 9, v[54:55]
	v_lshl_add_u64 v[58:59], v[26:27], 0, v[58:59]
	global_load_dword v31, v[56:57], off
	global_load_dword v33, v[36:37], off
	global_load_dword v35, v[58:59], off
	global_load_dword v51, v[38:39], off
	v_lshl_add_u64 v[36:37], v[26:27], 0, v[60:61]
	v_lshlrev_b64 v[38:39], 9, v[2:3]
	v_lshl_add_u64 v[52:53], v[26:27], 0, v[52:53]
	v_lshl_add_u64 v[54:55], v[26:27], 0, v[54:55]
	v_lshl_add_u64 v[38:39], v[26:27], 0, v[38:39]
	global_load_dword v2, v[36:37], off
	global_load_dword v64, v[52:53], off
	global_load_dword v65, v[38:39], off
	global_load_dword v66, v[54:55], off
	s_add_i32 s24, s24, 8
	s_add_i32 s23, s23, 8
	s_add_i32 s25, s25, -8
	v_add_u32_e32 v36, s26, v152
	v_add_u32_e32 v38, s27, v1
	v_add_u32_e32 v54, s27, v5
	v_add_u32_e32 v52, s26, v14
	v_add_u32_e32 v58, s27, v15
	v_add_u32_e32 v56, s26, v16
	v_add_u32_e32 v62, s27, v17
	v_add_u32_e32 v60, s26, v18
	s_cmp_lg_u32 s25, 0
	v_mad_u64_u32 v[36:37], s[26:27], v36, s33, v[4:5]
	v_mad_u64_u32 v[38:39], s[26:27], v38, s33, v[4:5]
	v_mad_u64_u32 v[52:53], s[26:27], v52, s33, v[4:5]
	v_mad_u64_u32 v[54:55], s[26:27], v54, s33, v[4:5]
	v_mad_u64_u32 v[56:57], s[26:27], v56, s33, v[4:5]
	v_mad_u64_u32 v[58:59], s[26:27], v58, s33, v[4:5]
	v_mad_u64_u32 v[60:61], s[26:27], v60, s33, v[4:5]
	v_mad_u64_u32 v[62:63], s[26:27], v62, s33, v[4:5]
	v_mov_b32_e32 v87, v3
	s_lshl_b32 s26, s24, 2
	s_lshl_b32 s27, s23, 2
	v_add_u32_e32 v86, s26, v28
	v_mov_b32_e32 v121, v3
	v_mov_b32_e32 v123, v3
	v_add_u32_e32 v120, s27, v19
	v_add_u32_e32 v122, s27, v23
	v_lshlrev_b64 v[140:141], 9, v[86:87]
	v_add_u32_e32 v86, s26, v30
	v_lshlrev_b64 v[120:121], 9, v[120:121]
	v_lshlrev_b64 v[122:123], 9, v[122:123]
	v_lshlrev_b64 v[142:143], 9, v[86:87]
	v_add_u32_e32 v86, s26, v32
	v_mov_b32_e32 v137, v3
	v_mov_b32_e32 v139, v3
	v_add_u32_e32 v136, s27, v25
	v_add_u32_e32 v138, s27, v29
	v_lshl_add_u64 v[140:141], v[26:27], 0, v[140:141]
	v_lshl_add_u64 v[120:121], v[26:27], 0, v[120:121]
	v_lshl_add_u64 v[122:123], v[26:27], 0, v[122:123]
	v_lshlrev_b64 v[144:145], 9, v[86:87]
	v_add_u32_e32 v86, s26, v34
	v_lshlrev_b64 v[136:137], 9, v[136:137]
	v_lshlrev_b64 v[138:139], 9, v[138:139]
	v_lshl_add_u64 v[142:143], v[26:27], 0, v[142:143]
	global_load_dword v115, v[140:141], off
	global_load_dword v117, v[120:121], off
	global_load_dword v119, v[142:143], off
	global_load_dword v135, v[122:123], off
	v_lshl_add_u64 v[120:121], v[26:27], 0, v[144:145]
	v_lshlrev_b64 v[122:123], 9, v[86:87]
	v_lshl_add_u64 v[136:137], v[26:27], 0, v[136:137]
	v_lshl_add_u64 v[138:139], v[26:27], 0, v[138:139]
	v_lshl_add_u64 v[122:123], v[26:27], 0, v[122:123]
	global_load_dword v86, v[120:121], off
	global_load_dword v148, v[136:137], off
	global_load_dword v149, v[122:123], off
	global_load_dword v150, v[138:139], off
	s_add_i32 s24, s24, 8
	s_add_i32 s23, s23, 8
	s_add_i32 s25, s25, -8
	v_add_u32_e32 v120, s26, v152
	v_add_u32_e32 v122, s27, v1
	v_add_u32_e32 v138, s27, v5
	v_add_u32_e32 v136, s26, v14
	v_add_u32_e32 v142, s27, v15
	v_add_u32_e32 v140, s26, v16
	v_add_u32_e32 v146, s27, v17
	v_add_u32_e32 v144, s26, v18
	s_cmp_lg_u32 s25, 0
	v_mad_u64_u32 v[120:121], s[26:27], v120, s33, v[4:5]
	v_mad_u64_u32 v[122:123], s[26:27], v122, s33, v[4:5]
	v_mad_u64_u32 v[136:137], s[26:27], v136, s33, v[4:5]
	v_mad_u64_u32 v[138:139], s[26:27], v138, s33, v[4:5]
	v_mad_u64_u32 v[140:141], s[26:27], v140, s33, v[4:5]
	v_mad_u64_u32 v[142:143], s[26:27], v142, s33, v[4:5]
	v_mad_u64_u32 v[144:145], s[26:27], v144, s33, v[4:5]
	v_mad_u64_u32 v[146:147], s[26:27], v146, s33, v[4:5]
	s_waitcnt vmcnt(15)
	ds_write_b32 v36, v31
	s_waitcnt vmcnt(14)
	ds_write_b32 v38, v33
	s_waitcnt vmcnt(13)
	ds_write_b32 v52, v35
	s_waitcnt vmcnt(12)
	ds_write_b32 v54, v51
	s_waitcnt vmcnt(11)
	ds_write_b32 v56, v2
	s_waitcnt vmcnt(10)
	ds_write_b32 v58, v64
	s_waitcnt vmcnt(9)
	ds_write_b32 v60, v65
	s_waitcnt vmcnt(8)
	ds_write_b32 v62, v66
	s_waitcnt vmcnt(7)
	ds_write_b32 v120, v115
	s_waitcnt vmcnt(6)
	ds_write_b32 v122, v117
	s_waitcnt vmcnt(5)
	ds_write_b32 v136, v119
	s_waitcnt vmcnt(4)
	ds_write_b32 v138, v135
	s_waitcnt vmcnt(3)
	ds_write_b32 v140, v86
	s_waitcnt vmcnt(2)
	ds_write_b32 v142, v148
	s_waitcnt vmcnt(1)
	ds_write_b32 v144, v149
	s_waitcnt vmcnt(0)
	ds_write_b32 v146, v150
	s_cbranch_scc1 .LBB0_64
	s_waitcnt lgkmcnt(0)
	s_barrier
	ds_read2_b32 v[26:27], v41 offset1:65
	ds_read2_b32 v[28:29], v41 offset0:130 offset1:195
	ds_read2_b32 v[30:31], v48 offset0:4 offset1:69
	v_add_u32_e32 v2, s22, v153
	s_lshl_b32 s18, s18, 1
	s_waitcnt lgkmcnt(2)
	v_cvt_pk_f16_f32 v26, v26, v27
	s_waitcnt lgkmcnt(1)
	v_cvt_pk_f16_f32 v27, v28, v29
	s_waitcnt lgkmcnt(0)
	v_cvt_pk_f16_f32 v28, v30, v31
	ds_read2_b32 v[30:31], v48 offset0:134 offset1:199
	ds_read2_b32 v[32:33], v49 offset0:8 offset1:73
	ds_read2_b32 v[34:35], v49 offset0:138 offset1:203
	ds_read2_b32 v[36:37], v50 offset0:12 offset1:77
	ds_read2_b32 v[38:39], v50 offset0:142 offset1:207
	s_waitcnt lgkmcnt(4)
	v_cvt_pk_f16_f32 v29, v30, v31
	v_mov_b32_e32 v25, v3
	s_waitcnt lgkmcnt(2)
	v_cvt_pk_f16_f32 v31, v34, v35
	v_lshlrev_b64 v[34:35], 12, v[2:3]
	v_lshl_add_u64 v[34:35], s[10:11], 0, v[34:35]
	v_lshl_add_u64 v[34:35], v[34:35], 0, s[18:19]
	v_lshl_add_u64 v[34:35], v[34:35], 0, v[24:25]
	s_mov_b64 s[24:25], -1
	v_cvt_pk_f16_f32 v30, v32, v33
	s_waitcnt lgkmcnt(1)
	v_cvt_pk_f16_f32 v32, v36, v37
	s_waitcnt lgkmcnt(0)
	v_cvt_pk_f16_f32 v33, v38, v39
	global_store_dwordx4 v[34:35], v[26:29], off
	global_store_dwordx4 v[34:35], v[30:33], off offset:16
	s_barrier

; DI unsigned pack2(float a, float b) { f32x2 v = {a, b}; bfx2 r = __builtin_convertvector(v, bfx2); return __builtin_bit_cast(unsigned, r); }
; DI void transpose_tile(const float* __restrict__ src, int ldsrc, u16* __restrict__ dst, int Kd, int k0, int n0, bool mapped, char* smem) {
;     ...
; #pragma unroll 4
;   for (int i = 0; i < 16; ++i) {
;     int k = (tid >> 6) + 4 * i;
;     float v = (sc >= 0) ? src[(size_t)(k0 + k) * ldsrc + sc] : 0.f;
;     s[k * 65 + nn] = v;
;   }
;   __syncthreads();
;   const int n = tid >> 2, kc = (tid & 3) * 16;
;   unsigned pk[8];
; #pragma unroll
;   for (int e = 0; e < 8; ++e) pk[e] = pack2(s[(kc + 2 * e) * 65 + n], s[(kc + 2 * e + 1) * 65 + n]);
;   uint4* d = (uint4*)(dst + (size_t)(n0 + n) * Kd + k0 + kc);
;   d[0] = make_uint4(pk[0], pk[1], pk[2], pk[3]);
;   d[1] = make_uint4(pk[4], pk[5], pk[6], pk[7]);
;   __syncthreads();
.LBB0_68:
	s_lshl_b32 s26, s24, 2
	s_lshl_b32 s27, s23, 2
	v_add_u32_e32 v2, s26, v28
	v_mov_b32_e32 v37, v3
	v_mov_b32_e32 v39, v3
	v_add_u32_e32 v36, s27, v19
	v_add_u32_e32 v38, s27, v23
	v_lshlrev_b64 v[56:57], 12, v[2:3]
	v_add_u32_e32 v2, s26, v30
	v_lshlrev_b64 v[36:37], 12, v[36:37]
	v_lshlrev_b64 v[38:39], 12, v[38:39]
	v_lshlrev_b64 v[58:59], 12, v[2:3]
	v_add_u32_e32 v2, s26, v32
	v_mov_b32_e32 v53, v3
	v_mov_b32_e32 v55, v3
	v_add_u32_e32 v52, s27, v25
	v_add_u32_e32 v54, s27, v29
	v_lshl_add_u64 v[56:57], v[26:27], 0, v[56:57]
	v_lshl_add_u64 v[36:37], v[26:27], 0, v[36:37]
	v_lshl_add_u64 v[38:39], v[26:27], 0, v[38:39]
	v_lshlrev_b64 v[60:61], 12, v[2:3]
	v_add_u32_e32 v2, s26, v34
	v_lshlrev_b64 v[52:53], 12, v[52:53]
	v_lshlrev_b64 v[54:55], 12, v[54:55]
	v_lshl_add_u64 v[58:59], v[26:27], 0, v[58:59]
	global_load_dword v31, v[56:57], off
	global_load_dword v33, v[36:37], off
	global_load_dword v35, v[58:59], off
	global_load_dword v51, v[38:39], off
	v_lshl_add_u64 v[36:37], v[26:27], 0, v[60:61]
	v_lshlrev_b64 v[38:39], 12, v[2:3]
	v_lshl_add_u64 v[52:53], v[26:27], 0, v[52:53]
	v_lshl_add_u64 v[54:55], v[26:27], 0, v[54:55]
	v_lshl_add_u64 v[38:39], v[26:27], 0, v[38:39]
	global_load_dword v2, v[36:37], off
	global_load_dword v64, v[52:53], off
	global_load_dword v65, v[38:39], off
	global_load_dword v66, v[54:55], off
	s_add_i32 s24, s24, 8
	s_add_i32 s23, s23, 8
	s_add_i32 s25, s25, -8
	v_add_u32_e32 v36, s26, v152
	v_add_u32_e32 v38, s27, v1
	v_add_u32_e32 v54, s27, v5
	v_add_u32_e32 v52, s26, v14
	v_add_u32_e32 v58, s27, v15
	v_add_u32_e32 v56, s26, v16
	v_add_u32_e32 v62, s27, v17
	v_add_u32_e32 v60, s26, v18
	s_cmp_lg_u32 s25, 0
	v_mad_u64_u32 v[36:37], s[26:27], v36, s33, v[4:5]
	v_mad_u64_u32 v[38:39], s[26:27], v38, s33, v[4:5]
	v_mad_u64_u32 v[52:53], s[26:27], v52, s33, v[4:5]
	v_mad_u64_u32 v[54:55], s[26:27], v54, s33, v[4:5]
	v_mad_u64_u32 v[56:57], s[26:27], v56, s33, v[4:5]
	v_mad_u64_u32 v[58:59], s[26:27], v58, s33, v[4:5]
	v_mad_u64_u32 v[60:61], s[26:27], v60, s33, v[4:5]
	v_mad_u64_u32 v[62:63], s[26:27], v62, s33, v[4:5]
	v_mov_b32_e32 v87, v3
	s_lshl_b32 s26, s24, 2
	s_lshl_b32 s27, s23, 2
	v_add_u32_e32 v86, s26, v28
	v_mov_b32_e32 v121, v3
	v_mov_b32_e32 v123, v3
	v_add_u32_e32 v120, s27, v19
	v_add_u32_e32 v122, s27, v23
	v_lshlrev_b64 v[140:141], 12, v[86:87]
	v_add_u32_e32 v86, s26, v30
	v_lshlrev_b64 v[120:121], 12, v[120:121]
	v_lshlrev_b64 v[122:123], 12, v[122:123]
	v_lshlrev_b64 v[142:143], 12, v[86:87]
	v_add_u32_e32 v86, s26, v32
	v_mov_b32_e32 v137, v3
	v_mov_b32_e32 v139, v3
	v_add_u32_e32 v136, s27, v25
	v_add_u32_e32 v138, s27, v29
	v_lshl_add_u64 v[140:141], v[26:27], 0, v[140:141]
	v_lshl_add_u64 v[120:121], v[26:27], 0, v[120:121]
	v_lshl_add_u64 v[122:123], v[26:27], 0, v[122:123]
	v_lshlrev_b64 v[144:145], 12, v[86:87]
	v_add_u32_e32 v86, s26, v34
	v_lshlrev_b64 v[136:137], 12, v[136:137]
	v_lshlrev_b64 v[138:139], 12, v[138:139]
	v_lshl_add_u64 v[142:143], v[26:27], 0, v[142:143]
	global_load_dword v115, v[140:141], off
	global_load_dword v117, v[120:121], off
	global_load_dword v119, v[142:143], off
	global_load_dword v135, v[122:123], off
	v_lshl_add_u64 v[120:121], v[26:27], 0, v[144:145]
	v_lshlrev_b64 v[122:123], 12, v[86:87]
	v_lshl_add_u64 v[136:137], v[26:27], 0, v[136:137]
	v_lshl_add_u64 v[138:139], v[26:27], 0, v[138:139]
	v_lshl_add_u64 v[122:123], v[26:27], 0, v[122:123]
	global_load_dword v86, v[120:121], off
	global_load_dword v148, v[136:137], off
	global_load_dword v149, v[122:123], off
	global_load_dword v150, v[138:139], off
	s_add_i32 s24, s24, 8
	s_add_i32 s23, s23, 8
	s_add_i32 s25, s25, -8
	v_add_u32_e32 v120, s26, v152
	v_add_u32_e32 v122, s27, v1
	v_add_u32_e32 v138, s27, v5
	v_add_u32_e32 v136, s26, v14
	v_add_u32_e32 v142, s27, v15
	v_add_u32_e32 v140, s26, v16
	v_add_u32_e32 v146, s27, v17
	v_add_u32_e32 v144, s26, v18
	s_cmp_lg_u32 s25, 0
	v_mad_u64_u32 v[120:121], s[26:27], v120, s33, v[4:5]
	v_mad_u64_u32 v[122:123], s[26:27], v122, s33, v[4:5]
	v_mad_u64_u32 v[136:137], s[26:27], v136, s33, v[4:5]
	v_mad_u64_u32 v[138:139], s[26:27], v138, s33, v[4:5]
	v_mad_u64_u32 v[140:141], s[26:27], v140, s33, v[4:5]
	v_mad_u64_u32 v[142:143], s[26:27], v142, s33, v[4:5]
	v_mad_u64_u32 v[144:145], s[26:27], v144, s33, v[4:5]
	v_mad_u64_u32 v[146:147], s[26:27], v146, s33, v[4:5]
	s_waitcnt vmcnt(15)
	ds_write_b32 v36, v31
	s_waitcnt vmcnt(14)
	ds_write_b32 v38, v33
	s_waitcnt vmcnt(13)
	ds_write_b32 v52, v35
	s_waitcnt vmcnt(12)
	ds_write_b32 v54, v51
	s_waitcnt vmcnt(11)
	ds_write_b32 v56, v2
	s_waitcnt vmcnt(10)
	ds_write_b32 v58, v64
	s_waitcnt vmcnt(9)
	ds_write_b32 v60, v65
	s_waitcnt vmcnt(8)
	ds_write_b32 v62, v66
	s_waitcnt vmcnt(7)
	ds_write_b32 v120, v115
	s_waitcnt vmcnt(6)
	ds_write_b32 v122, v117
	s_waitcnt vmcnt(5)
	ds_write_b32 v136, v119
	s_waitcnt vmcnt(4)
	ds_write_b32 v138, v135
	s_waitcnt vmcnt(3)
	ds_write_b32 v140, v86
	s_waitcnt vmcnt(2)
	ds_write_b32 v142, v148
	s_waitcnt vmcnt(1)
	ds_write_b32 v144, v149
	s_waitcnt vmcnt(0)
	ds_write_b32 v146, v150
	s_cbranch_scc1 .LBB0_68
	s_waitcnt lgkmcnt(0)
	s_barrier
	ds_read2_b32 v[26:27], v41 offset1:65
	ds_read2_b32 v[28:29], v41 offset0:130 offset1:195
	ds_read2_b32 v[30:31], v48 offset0:4 offset1:69
	v_add_u32_e32 v2, s22, v153
	s_lshl_b32 s18, s18, 1
	s_waitcnt lgkmcnt(2)
	v_cvt_pk_f16_f32 v26, v26, v27
	s_waitcnt lgkmcnt(1)
	v_cvt_pk_f16_f32 v27, v28, v29
	s_waitcnt lgkmcnt(0)
	v_cvt_pk_f16_f32 v28, v30, v31
	ds_read2_b32 v[30:31], v48 offset0:134 offset1:199
	ds_read2_b32 v[32:33], v49 offset0:8 offset1:73
	ds_read2_b32 v[34:35], v49 offset0:138 offset1:203
	ds_read2_b32 v[36:37], v50 offset0:12 offset1:77
	ds_read2_b32 v[38:39], v50 offset0:142 offset1:207
	s_waitcnt lgkmcnt(4)
	v_cvt_pk_f16_f32 v29, v30, v31
	v_mov_b32_e32 v25, v3
	s_waitcnt lgkmcnt(2)
	v_cvt_pk_f16_f32 v31, v34, v35
	v_lshlrev_b64 v[34:35], 13, v[2:3]
	v_lshl_add_u64 v[34:35], s[12:13], 0, v[34:35]
	v_lshl_add_u64 v[34:35], v[34:35], 0, s[18:19]
	v_lshl_add_u64 v[34:35], v[34:35], 0, v[24:25]
	s_mov_b64 s[24:25], -1
	v_cvt_pk_f16_f32 v30, v32, v33
	s_waitcnt lgkmcnt(1)
	v_cvt_pk_f16_f32 v32, v36, v37
	s_waitcnt lgkmcnt(0)
	v_cvt_pk_f16_f32 v33, v38, v39
	global_store_dwordx4 v[34:35], v[26:29], off
	global_store_dwordx4 v[34:35], v[30:33], off offset:16
	s_barrier

; DI unsigned pack2(float a, float b) { f32x2 v = {a, b}; bfx2 r = __builtin_convertvector(v, bfx2); return __builtin_bit_cast(unsigned, r); }
; DI void transpose_tile(const float* __restrict__ src, int ldsrc, u16* __restrict__ dst, int Kd, int k0, int n0, bool mapped, char* smem) {
;     ...
; #pragma unroll 4
;   for (int i = 0; i < 16; ++i) {
;     int k = (tid >> 6) + 4 * i;
;     float v = (sc >= 0) ? src[(size_t)(k0 + k) * ldsrc + sc] : 0.f;
;     s[k * 65 + nn] = v;
;   }
;   __syncthreads();
;   const int n = tid >> 2, kc = (tid & 3) * 16;
;   unsigned pk[8];
; #pragma unroll
;   for (int e = 0; e < 8; ++e) pk[e] = pack2(s[(kc + 2 * e) * 65 + n], s[(kc + 2 * e + 1) * 65 + n]);
;   uint4* d = (uint4*)(dst + (size_t)(n0 + n) * Kd + k0 + kc);
;   d[0] = make_uint4(pk[0], pk[1], pk[2], pk[3]);
;   d[1] = make_uint4(pk[4], pk[5], pk[6], pk[7]);
;   __syncthreads();
.LBB0_72:
	s_lshl_b32 s26, s24, 2
	s_lshl_b32 s27, s23, 2
	v_add_u32_e32 v2, s26, v28
	v_mov_b32_e32 v37, v3
	v_mov_b32_e32 v39, v3
	v_add_u32_e32 v36, s27, v19
	v_add_u32_e32 v38, s27, v23
	v_lshlrev_b64 v[56:57], 14, v[2:3]
	v_add_u32_e32 v2, s26, v30
	v_lshlrev_b64 v[36:37], 14, v[36:37]
	v_lshlrev_b64 v[38:39], 14, v[38:39]
	v_lshlrev_b64 v[58:59], 14, v[2:3]
	v_add_u32_e32 v2, s26, v32
	v_mov_b32_e32 v53, v3
	v_mov_b32_e32 v55, v3
	v_add_u32_e32 v52, s27, v25
	v_add_u32_e32 v54, s27, v29
	v_lshl_add_u64 v[56:57], v[26:27], 0, v[56:57]
	v_lshl_add_u64 v[36:37], v[26:27], 0, v[36:37]
	v_lshl_add_u64 v[38:39], v[26:27], 0, v[38:39]
	v_lshlrev_b64 v[60:61], 14, v[2:3]
	v_add_u32_e32 v2, s26, v34
	v_lshlrev_b64 v[52:53], 14, v[52:53]
	v_lshlrev_b64 v[54:55], 14, v[54:55]
	v_lshl_add_u64 v[58:59], v[26:27], 0, v[58:59]
	global_load_dword v31, v[56:57], off
	global_load_dword v33, v[36:37], off
	global_load_dword v35, v[58:59], off
	global_load_dword v51, v[38:39], off
	v_lshl_add_u64 v[36:37], v[26:27], 0, v[60:61]
	v_lshlrev_b64 v[38:39], 14, v[2:3]
	v_lshl_add_u64 v[52:53], v[26:27], 0, v[52:53]
	v_lshl_add_u64 v[54:55], v[26:27], 0, v[54:55]
	v_lshl_add_u64 v[38:39], v[26:27], 0, v[38:39]
	global_load_dword v2, v[36:37], off
	global_load_dword v64, v[52:53], off
	global_load_dword v65, v[38:39], off
	global_load_dword v66, v[54:55], off
	s_add_i32 s24, s24, 8
	s_add_i32 s23, s23, 8
	s_add_i32 s25, s25, -8
	v_add_u32_e32 v36, s26, v152
	v_add_u32_e32 v38, s27, v1
	v_add_u32_e32 v54, s27, v5
	v_add_u32_e32 v52, s26, v14
	v_add_u32_e32 v58, s27, v15
	v_add_u32_e32 v56, s26, v16
	v_add_u32_e32 v62, s27, v17
	v_add_u32_e32 v60, s26, v18
	s_cmp_lg_u32 s25, 0
	v_mad_u64_u32 v[36:37], s[26:27], v36, s33, v[4:5]
	v_mad_u64_u32 v[38:39], s[26:27], v38, s33, v[4:5]
	v_mad_u64_u32 v[52:53], s[26:27], v52, s33, v[4:5]
	v_mad_u64_u32 v[54:55], s[26:27], v54, s33, v[4:5]
	v_mad_u64_u32 v[56:57], s[26:27], v56, s33, v[4:5]
	v_mad_u64_u32 v[58:59], s[26:27], v58, s33, v[4:5]
	v_mad_u64_u32 v[60:61], s[26:27], v60, s33, v[4:5]
	v_mad_u64_u32 v[62:63], s[26:27], v62, s33, v[4:5]
	v_mov_b32_e32 v87, v3
	s_lshl_b32 s26, s24, 2
	s_lshl_b32 s27, s23, 2
	v_add_u32_e32 v86, s26, v28
	v_mov_b32_e32 v121, v3
	v_mov_b32_e32 v123, v3
	v_add_u32_e32 v120, s27, v19
	v_add_u32_e32 v122, s27, v23
	v_lshlrev_b64 v[140:141], 14, v[86:87]
	v_add_u32_e32 v86, s26, v30
	v_lshlrev_b64 v[120:121], 14, v[120:121]
	v_lshlrev_b64 v[122:123], 14, v[122:123]
	v_lshlrev_b64 v[142:143], 14, v[86:87]
	v_add_u32_e32 v86, s26, v32
	v_mov_b32_e32 v137, v3
	v_mov_b32_e32 v139, v3
	v_add_u32_e32 v136, s27, v25
	v_add_u32_e32 v138, s27, v29
	v_lshl_add_u64 v[140:141], v[26:27], 0, v[140:141]
	v_lshl_add_u64 v[120:121], v[26:27], 0, v[120:121]
	v_lshl_add_u64 v[122:123], v[26:27], 0, v[122:123]
	v_lshlrev_b64 v[144:145], 14, v[86:87]
	v_add_u32_e32 v86, s26, v34
	v_lshlrev_b64 v[136:137], 14, v[136:137]
	v_lshlrev_b64 v[138:139], 14, v[138:139]
	v_lshl_add_u64 v[142:143], v[26:27], 0, v[142:143]
	global_load_dword v115, v[140:141], off
	global_load_dword v117, v[120:121], off
	global_load_dword v119, v[142:143], off
	global_load_dword v135, v[122:123], off
	v_lshl_add_u64 v[120:121], v[26:27], 0, v[144:145]
	v_lshlrev_b64 v[122:123], 14, v[86:87]
	v_lshl_add_u64 v[136:137], v[26:27], 0, v[136:137]
	v_lshl_add_u64 v[138:139], v[26:27], 0, v[138:139]
	v_lshl_add_u64 v[122:123], v[26:27], 0, v[122:123]
	global_load_dword v86, v[120:121], off
	global_load_dword v148, v[136:137], off
	global_load_dword v149, v[122:123], off
	global_load_dword v150, v[138:139], off
	s_add_i32 s24, s24, 8
	s_add_i32 s23, s23, 8
	s_add_i32 s25, s25, -8
	v_add_u32_e32 v120, s26, v152
	v_add_u32_e32 v122, s27, v1
	v_add_u32_e32 v138, s27, v5
	v_add_u32_e32 v136, s26, v14
	v_add_u32_e32 v142, s27, v15
	v_add_u32_e32 v140, s26, v16
	v_add_u32_e32 v146, s27, v17
	v_add_u32_e32 v144, s26, v18
	s_cmp_lg_u32 s25, 0
	v_mad_u64_u32 v[120:121], s[26:27], v120, s33, v[4:5]
	v_mad_u64_u32 v[122:123], s[26:27], v122, s33, v[4:5]
	v_mad_u64_u32 v[136:137], s[26:27], v136, s33, v[4:5]
	v_mad_u64_u32 v[138:139], s[26:27], v138, s33, v[4:5]
	v_mad_u64_u32 v[140:141], s[26:27], v140, s33, v[4:5]
	v_mad_u64_u32 v[142:143], s[26:27], v142, s33, v[4:5]
	v_mad_u64_u32 v[144:145], s[26:27], v144, s33, v[4:5]
	v_mad_u64_u32 v[146:147], s[26:27], v146, s33, v[4:5]
	s_waitcnt vmcnt(15)
	ds_write_b32 v36, v31
	s_waitcnt vmcnt(14)
	ds_write_b32 v38, v33
	s_waitcnt vmcnt(13)
	ds_write_b32 v52, v35
	s_waitcnt vmcnt(12)
	ds_write_b32 v54, v51
	s_waitcnt vmcnt(11)
	ds_write_b32 v56, v2
	s_waitcnt vmcnt(10)
	ds_write_b32 v58, v64
	s_waitcnt vmcnt(9)
	ds_write_b32 v60, v65
	s_waitcnt vmcnt(8)
	ds_write_b32 v62, v66
	s_waitcnt vmcnt(7)
	ds_write_b32 v120, v115
	s_waitcnt vmcnt(6)
	ds_write_b32 v122, v117
	s_waitcnt vmcnt(5)
	ds_write_b32 v136, v119
	s_waitcnt vmcnt(4)
	ds_write_b32 v138, v135
	s_waitcnt vmcnt(3)
	ds_write_b32 v140, v86
	s_waitcnt vmcnt(2)
	ds_write_b32 v142, v148
	s_waitcnt vmcnt(1)
	ds_write_b32 v144, v149
	s_waitcnt vmcnt(0)
	ds_write_b32 v146, v150
	s_cbranch_scc1 .LBB0_72
	s_waitcnt lgkmcnt(0)
	s_barrier
	ds_read2_b32 v[26:27], v41 offset1:65
	ds_read2_b32 v[28:29], v41 offset0:130 offset1:195
	ds_read2_b32 v[30:31], v48 offset0:4 offset1:69
	v_add_u32_e32 v2, s22, v153
	s_lshl_b32 s18, s18, 1
	s_waitcnt lgkmcnt(2)
	v_cvt_pk_f16_f32 v26, v26, v27
	s_waitcnt lgkmcnt(1)
	v_cvt_pk_f16_f32 v27, v28, v29
	s_waitcnt lgkmcnt(0)
	v_cvt_pk_f16_f32 v28, v30, v31
	ds_read2_b32 v[30:31], v48 offset0:134 offset1:199
	ds_read2_b32 v[32:33], v49 offset0:8 offset1:73
	ds_read2_b32 v[34:35], v49 offset0:138 offset1:203
	ds_read2_b32 v[36:37], v50 offset0:12 offset1:77
	ds_read2_b32 v[38:39], v50 offset0:142 offset1:207
	s_waitcnt lgkmcnt(4)
	v_cvt_pk_f16_f32 v29, v30, v31
	v_mov_b32_e32 v25, v3
	s_waitcnt lgkmcnt(2)
	v_cvt_pk_f16_f32 v31, v34, v35
	v_lshlrev_b64 v[34:35], 11, v[2:3]
	v_lshl_add_u64 v[34:35], s[14:15], 0, v[34:35]
	v_lshl_add_u64 v[34:35], v[34:35], 0, s[18:19]
	v_lshl_add_u64 v[34:35], v[34:35], 0, v[24:25]
	s_mov_b64 s[24:25], -1
	v_cvt_pk_f16_f32 v30, v32, v33
	s_waitcnt lgkmcnt(1)
	v_cvt_pk_f16_f32 v32, v36, v37
	s_waitcnt lgkmcnt(0)
	v_cvt_pk_f16_f32 v33, v38, v39
	global_store_dwordx4 v[34:35], v[26:29], off
	global_store_dwordx4 v[34:35], v[30:33], off offset:16
	s_barrier

; DI unsigned pack2(float a, float b) { f32x2 v = {a, b}; bfx2 r = __builtin_convertvector(v, bfx2); return __builtin_bit_cast(unsigned, r); }
; DI void transpose_tile(const float* __restrict__ src, int ldsrc, u16* __restrict__ dst, int Kd, int k0, int n0, bool mapped, char* smem) {
;     ...
; #pragma unroll 4
;   for (int i = 0; i < 16; ++i) {
;     int k = (tid >> 6) + 4 * i;
;     float v = (sc >= 0) ? src[(size_t)(k0 + k) * ldsrc + sc] : 0.f;
;     s[k * 65 + nn] = v;
;   }
;   __syncthreads();
;   const int n = tid >> 2, kc = (tid & 3) * 16;
;   unsigned pk[8];
; #pragma unroll
;   for (int e = 0; e < 8; ++e) pk[e] = pack2(s[(kc + 2 * e) * 65 + n], s[(kc + 2 * e + 1) * 65 + n]);
;   uint4* d = (uint4*)(dst + (size_t)(n0 + n) * Kd + k0 + kc);
;   d[0] = make_uint4(pk[0], pk[1], pk[2], pk[3]);
;   d[1] = make_uint4(pk[4], pk[5], pk[6], pk[7]);
;   __syncthreads();
.LBB0_76:
	s_lshl_b32 s26, s24, 2
	s_lshl_b32 s27, s23, 2
	v_add_u32_e32 v2, s26, v28
	v_mov_b32_e32 v37, v3
	v_mov_b32_e32 v39, v3
	v_add_u32_e32 v36, s27, v19
	v_add_u32_e32 v38, s27, v23
	v_lshlrev_b64 v[56:57], 12, v[2:3]
	v_add_u32_e32 v2, s26, v30
	v_lshlrev_b64 v[36:37], 12, v[36:37]
	v_lshlrev_b64 v[38:39], 12, v[38:39]
	v_lshlrev_b64 v[58:59], 12, v[2:3]
	v_add_u32_e32 v2, s26, v32
	v_mov_b32_e32 v53, v3
	v_mov_b32_e32 v55, v3
	v_add_u32_e32 v52, s27, v25
	v_add_u32_e32 v54, s27, v29
	v_lshl_add_u64 v[56:57], v[26:27], 0, v[56:57]
	v_lshl_add_u64 v[36:37], v[26:27], 0, v[36:37]
	v_lshl_add_u64 v[38:39], v[26:27], 0, v[38:39]
	v_lshlrev_b64 v[60:61], 12, v[2:3]
	v_add_u32_e32 v2, s26, v34
	v_lshlrev_b64 v[52:53], 12, v[52:53]
	v_lshlrev_b64 v[54:55], 12, v[54:55]
	v_lshl_add_u64 v[58:59], v[26:27], 0, v[58:59]
	global_load_dword v31, v[56:57], off
	global_load_dword v33, v[36:37], off
	global_load_dword v35, v[58:59], off
	global_load_dword v51, v[38:39], off
	v_lshl_add_u64 v[36:37], v[26:27], 0, v[60:61]
	v_lshlrev_b64 v[38:39], 12, v[2:3]
	v_lshl_add_u64 v[52:53], v[26:27], 0, v[52:53]
	v_lshl_add_u64 v[54:55], v[26:27], 0, v[54:55]
	v_lshl_add_u64 v[38:39], v[26:27], 0, v[38:39]
	global_load_dword v2, v[36:37], off
	global_load_dword v64, v[52:53], off
	global_load_dword v65, v[38:39], off
	global_load_dword v66, v[54:55], off
	s_add_i32 s24, s24, 8
	s_add_i32 s23, s23, 8
	s_add_i32 s25, s25, -8
	v_add_u32_e32 v36, s26, v152
	v_add_u32_e32 v38, s27, v1
	v_add_u32_e32 v54, s27, v5
	v_add_u32_e32 v52, s26, v14
	v_add_u32_e32 v58, s27, v15
	v_add_u32_e32 v56, s26, v16
	v_add_u32_e32 v62, s27, v17
	v_add_u32_e32 v60, s26, v18
	s_cmp_lg_u32 s25, 0
	v_mad_u64_u32 v[36:37], s[26:27], v36, s33, v[4:5]
	v_mad_u64_u32 v[38:39], s[26:27], v38, s33, v[4:5]
	v_mad_u64_u32 v[52:53], s[26:27], v52, s33, v[4:5]
	v_mad_u64_u32 v[54:55], s[26:27], v54, s33, v[4:5]
	v_mad_u64_u32 v[56:57], s[26:27], v56, s33, v[4:5]
	v_mad_u64_u32 v[58:59], s[26:27], v58, s33, v[4:5]
	v_mad_u64_u32 v[60:61], s[26:27], v60, s33, v[4:5]
	v_mad_u64_u32 v[62:63], s[26:27], v62, s33, v[4:5]
	v_mov_b32_e32 v87, v3
	s_lshl_b32 s26, s24, 2
	s_lshl_b32 s27, s23, 2
	v_add_u32_e32 v86, s26, v28
	v_mov_b32_e32 v121, v3
	v_mov_b32_e32 v123, v3
	v_add_u32_e32 v120, s27, v19
	v_add_u32_e32 v122, s27, v23
	v_lshlrev_b64 v[140:141], 12, v[86:87]
	v_add_u32_e32 v86, s26, v30
	v_lshlrev_b64 v[120:121], 12, v[120:121]
	v_lshlrev_b64 v[122:123], 12, v[122:123]
	v_lshlrev_b64 v[142:143], 12, v[86:87]
	v_add_u32_e32 v86, s26, v32
	v_mov_b32_e32 v137, v3
	v_mov_b32_e32 v139, v3
	v_add_u32_e32 v136, s27, v25
	v_add_u32_e32 v138, s27, v29
	v_lshl_add_u64 v[140:141], v[26:27], 0, v[140:141]
	v_lshl_add_u64 v[120:121], v[26:27], 0, v[120:121]
	v_lshl_add_u64 v[122:123], v[26:27], 0, v[122:123]
	v_lshlrev_b64 v[144:145], 12, v[86:87]
	v_add_u32_e32 v86, s26, v34
	v_lshlrev_b64 v[136:137], 12, v[136:137]
	v_lshlrev_b64 v[138:139], 12, v[138:139]
	v_lshl_add_u64 v[142:143], v[26:27], 0, v[142:143]
	global_load_dword v115, v[140:141], off
	global_load_dword v117, v[120:121], off
	global_load_dword v119, v[142:143], off
	global_load_dword v135, v[122:123], off
	v_lshl_add_u64 v[120:121], v[26:27], 0, v[144:145]
	v_lshlrev_b64 v[122:123], 12, v[86:87]
	v_lshl_add_u64 v[136:137], v[26:27], 0, v[136:137]
	v_lshl_add_u64 v[138:139], v[26:27], 0, v[138:139]
	v_lshl_add_u64 v[122:123], v[26:27], 0, v[122:123]
	global_load_dword v86, v[120:121], off
	global_load_dword v148, v[136:137], off
	global_load_dword v149, v[122:123], off
	global_load_dword v150, v[138:139], off
	s_add_i32 s24, s24, 8
	s_add_i32 s23, s23, 8
	s_add_i32 s25, s25, -8
	v_add_u32_e32 v120, s26, v152
	v_add_u32_e32 v122, s27, v1
	v_add_u32_e32 v138, s27, v5
	v_add_u32_e32 v136, s26, v14
	v_add_u32_e32 v142, s27, v15
	v_add_u32_e32 v140, s26, v16
	v_add_u32_e32 v146, s27, v17
	v_add_u32_e32 v144, s26, v18
	s_cmp_lg_u32 s25, 0
	v_mad_u64_u32 v[120:121], s[26:27], v120, s33, v[4:5]
	v_mad_u64_u32 v[122:123], s[26:27], v122, s33, v[4:5]
	v_mad_u64_u32 v[136:137], s[26:27], v136, s33, v[4:5]
	v_mad_u64_u32 v[138:139], s[26:27], v138, s33, v[4:5]
	v_mad_u64_u32 v[140:141], s[26:27], v140, s33, v[4:5]
	v_mad_u64_u32 v[142:143], s[26:27], v142, s33, v[4:5]
	v_mad_u64_u32 v[144:145], s[26:27], v144, s33, v[4:5]
	v_mad_u64_u32 v[146:147], s[26:27], v146, s33, v[4:5]
	s_waitcnt vmcnt(15)
	ds_write_b32 v36, v31
	s_waitcnt vmcnt(14)
	ds_write_b32 v38, v33
	s_waitcnt vmcnt(13)
	ds_write_b32 v52, v35
	s_waitcnt vmcnt(12)
	ds_write_b32 v54, v51
	s_waitcnt vmcnt(11)
	ds_write_b32 v56, v2
	s_waitcnt vmcnt(10)
	ds_write_b32 v58, v64
	s_waitcnt vmcnt(9)
	ds_write_b32 v60, v65
	s_waitcnt vmcnt(8)
	ds_write_b32 v62, v66
	s_waitcnt vmcnt(7)
	ds_write_b32 v120, v115
	s_waitcnt vmcnt(6)
	ds_write_b32 v122, v117
	s_waitcnt vmcnt(5)
	ds_write_b32 v136, v119
	s_waitcnt vmcnt(4)
	ds_write_b32 v138, v135
	s_waitcnt vmcnt(3)
	ds_write_b32 v140, v86
	s_waitcnt vmcnt(2)
	ds_write_b32 v142, v148
	s_waitcnt vmcnt(1)
	ds_write_b32 v144, v149
	s_waitcnt vmcnt(0)
	ds_write_b32 v146, v150
	s_cbranch_scc1 .LBB0_76
	s_waitcnt lgkmcnt(0)
	s_barrier
	ds_read2_b32 v[26:27], v41 offset1:65
	ds_read2_b32 v[28:29], v41 offset0:130 offset1:195
	ds_read2_b32 v[30:31], v48 offset0:4 offset1:69
	v_add_u32_e32 v2, s22, v153
	s_lshl_b32 s18, s18, 1
	s_waitcnt lgkmcnt(2)
	v_cvt_pk_f16_f32 v26, v26, v27
	s_waitcnt lgkmcnt(1)
	v_cvt_pk_f16_f32 v27, v28, v29
	s_waitcnt lgkmcnt(0)
	v_cvt_pk_f16_f32 v28, v30, v31
	ds_read2_b32 v[30:31], v48 offset0:134 offset1:199
	ds_read2_b32 v[32:33], v49 offset0:8 offset1:73
	ds_read2_b32 v[34:35], v49 offset0:138 offset1:203
	ds_read2_b32 v[36:37], v50 offset0:12 offset1:77
	ds_read2_b32 v[38:39], v50 offset0:142 offset1:207
	s_waitcnt lgkmcnt(4)
	v_cvt_pk_f16_f32 v29, v30, v31
	v_mov_b32_e32 v25, v3
	s_waitcnt lgkmcnt(2)
	v_cvt_pk_f16_f32 v31, v34, v35
	v_lshlrev_b64 v[34:35], 11, v[2:3]
	v_lshl_add_u64 v[34:35], s[16:17], 0, v[34:35]
	v_lshl_add_u64 v[34:35], v[34:35], 0, s[18:19]
	v_lshl_add_u64 v[34:35], v[34:35], 0, v[24:25]
	s_mov_b64 s[24:25], -1
	v_cvt_pk_f16_f32 v30, v32, v33
	s_waitcnt lgkmcnt(1)
	v_cvt_pk_f16_f32 v32, v36, v37
	s_waitcnt lgkmcnt(0)
	v_cvt_pk_f16_f32 v33, v38, v39
	global_store_dwordx4 v[34:35], v[26:29], off
	global_store_dwordx4 v[34:35], v[30:33], off offset:16
	s_barrier
